# windowed attention: K/V staging registers alternate by tile parity instead of copy-rotation, so tile loads stay in flight for two tiles (counted vmcnt(2))
# speedup vs baseline: 1.0111x; 1.0001x over previous
; #define LAS __attribute__((address_space(3)))
; DI void win_mfma_phase(const Args& A, int wave_s, int l, bool need_ctx, LAS unsigned char* lds) {
;     ...
;         float ls = 0.f;
;         v4u kreg, vreg, kreg2, vreg2;
;         auto tile_row = [&](int it) -> int { return it < nloc ? b * LSEQ + t0 + 64 * (tfirst + it - 2) : NLAT + b * LCTX + 64 * (it - nloc); };
;         { const bf16* kr = C.P + (size_t)(tile_row(0) + srow) * INW; kreg = *(const v4u*)(kr + CA_K + kv * 64 + sch * 8); vreg = *(const v4u*)(kr + CA_V + kv * 64 + sch * 8); }
;         { const bf16* kr = C.P + (size_t)(tile_row(1) + srow) * INW; kreg2 = *(const v4u*)(kr + CA_K + kv * 64 + sch * 8); vreg2 = *(const v4u*)(kr + CA_V + kv * 64 + sch * 8); }
;         __syncthreads();
;         *(LAS v4u*)(lds + srow * KV_PITCH + sch * 16) = kreg; *(LAS v4u*)(lds + 2 * KV_IMG + srow * KV_PITCH + sch * 16) = vreg;
;         kreg = kreg2; vreg = vreg2;
;         __syncthreads();
;         for (int it = 0; it < ntiles; ++it) {
.LBB0_319:
	s_lshl_b32 s11, s12, 6
	v_add_u32_e32 v1, s17, v125
	v_mov_b64_e32 v[10:11], s[84:85]
	v_mad_i64_i32 v[10:11], s[4:5], v1, s77, v[10:11]
	s_lshl_b32 s96, s11, 1
	v_lshl_add_u64 v[10:11], v[10:11], 0, s[96:97]
	v_lshl_add_u64 v[10:11], v[10:11], 0, v[160:161]
	global_load_dwordx4 v[100:103], v[10:11], off offset:1024
	global_load_dwordx4 v[96:99], v[10:11], off offset:1280
	s_add_i32 s4, s14, s15
	v_mov_b32_e32 v132, 0
	v_ashrrev_i32_e32 v121, 31, v120
	s_lshl_b32 s11, s7, 6
	s_add_i32 s12, s10, 4
	s_add_i32 s13, s13, 0x8000
	s_mov_b32 s14, 0
	s_sub_i32 s15, 0, s10
	v_subrev_u32_e32 v131, s16, v130
	v_mov_b32_e32 v48, 0
	v_mov_b32_e32 v32, 0
	s_add_i32 s16, s4, 0xffffff80
	v_mov_b32_e32 v49, v132
	v_mov_b32_e32 v50, v132
	v_mov_b32_e32 v51, v132
	v_mov_b32_e32 v52, v132
	v_mov_b32_e32 v53, v132
	v_mov_b32_e32 v54, v132
	v_mov_b32_e32 v55, v132
	v_mov_b32_e32 v56, v132
	v_mov_b32_e32 v57, v132
	v_mov_b32_e32 v58, v132
	v_mov_b32_e32 v59, v132
	v_mov_b32_e32 v60, v132
	v_mov_b32_e32 v61, v132
	v_mov_b32_e32 v62, v132
	v_mov_b32_e32 v63, v132
	v_mov_b32_e32 v33, v132
	v_mov_b32_e32 v34, v132
	v_mov_b32_e32 v35, v132
	v_mov_b32_e32 v36, v132
	v_mov_b32_e32 v37, v132
	v_mov_b32_e32 v38, v132
	v_mov_b32_e32 v39, v132
	v_mov_b32_e32 v40, v132
	v_mov_b32_e32 v41, v132
	v_mov_b32_e32 v42, v132
	v_mov_b32_e32 v43, v132
	v_mov_b32_e32 v44, v132
	v_mov_b32_e32 v45, v132
	v_mov_b32_e32 v46, v132
	v_lshl_add_u64 v[122:123], v[118:119], 0, s[96:97]
	v_mov_b32_e32 v47, v132
	s_barrier
	s_waitcnt vmcnt(3)
	ds_write_b128 v127, v[2:5]
	s_waitcnt vmcnt(2)
	ds_write_b128 v127, v[6:9] offset:18432
	s_waitcnt lgkmcnt(0)
	s_barrier
	s_branch .LBB0_321

; #define LAS __attribute__((address_space(3)))
; #define MFMA32(a, b, c) __builtin_amdgcn_mfma_f32_32x32x16_bf16((a), (b), (c), 0, 0, 0)
; #define PACK8(x, s) __builtin_bit_cast(bf16x8, (v4u){pkbf((x)[8 * (s)], (x)[8 * (s) + 1]), pkbf((x)[8 * (s) + 2], (x)[8 * (s) + 3]), pkbf((x)[8 * (s) + 4], (x)[8 * (s) + 5]), pkbf((x)[8 * (s) + 6], (x)[8 * (s) + 7])})
; DI void win_mfma_phase(const Args& A, int wave_s, int l, bool need_ctx, LAS unsigned char* lds) {
;     ...
;         for (int it = 0; it < ntiles; ++it) {
;             const int cur = it & 1;
;             if (it + 2 < ntiles) { const bf16* kr = C.P + (size_t)(tile_row(it + 2) + srow) * INW; kreg2 = *(const v4u*)(kr + CA_K + kv * 64 + sch * 8); vreg2 = *(const v4u*)(kr + CA_V + kv * 64 + sch * 8); }
;             LAS unsigned char* Kb = lds + cur * KV_IMG; LAS unsigned char* Vb = lds + 2 * KV_IMG + cur * KV_IMG;
;             const bool local = it < nloc; const int tk0 = t0 + 64 * (tfirst + it - 2);
;             const bool edge = local && (tfirst + it == 0 || tfirst + it == 4);
; #pragma unroll
;             for (int sub = 0; sub < 2; ++sub) {
;                 f32x16 S;
; #pragma unroll
;                 for (int i = 0; i < 16; ++i) S[i] = -Mb2;
; #pragma unroll
;                 for (int s = 0; s < 4; ++s) { const bf16x8 kf = *(LAS bf16x8*)(Kb + (32 * sub + r) * KV_PITCH + s * 32 + h * 16); S = MFMA32(kf, Qf[s], S); }
;                 float t = 0.f;
; #pragma unroll
;                 for (int i = 0; i < 16; ++i) { float e = __builtin_amdgcn_exp2f(S[i]);
;                     if (edge) { const int tk = tk0 + 32 * sub + (i & 3) + 8 * (i >> 2) + 4 * h; const int d = tq - tk; e = (d > 128 || d < -128) ? 0.f : e; }
;                     S[i] = e; t += e; }
;                 ls += t;
;                 const bf16x8 P0 = PACK8(S, 0), P1 = PACK8(S, 1);
; #pragma unroll
;                 for (int mt = 0; mt < 2; ++mt) {
;                     const bf16x8 v0 = tr_pair(Vb + (32 * sub) * KV_PITCH + voff + mt * 64);
;                     const bf16x8 v1 = tr_pair(Vb + (32 * sub + 16) * KV_PITCH + voff + mt * 64);
;                     O[mt] = MFMA32(v0, P0, O[mt]); O[mt] = MFMA32(v1, P1, O[mt]);
;                 }
.LBB0_321:
	s_add_i32 s4, s14, 2
	s_cmp_ge_i32 s4, s12
	s_cbranch_scc1 .LBB0_323
	s_cmp_lt_i32 s4, s10
	s_cselect_b32 s4, s6, s15
	s_cselect_b32 s5, s16, s13
	s_add_i32 s4, s4, s14
	s_lshl_b32 s4, s4, 6
	s_add_i32 s4, s4, s5
	s_addk_i32 s4, 0x80
	v_add_u32_e32 v1, s4, v125
	v_mad_i64_i32 v[2:3], s[4:5], v1, s77, v[122:123]
	s_bitcmp1_b32 s14, 0
	s_cbranch_scc1 .Lwin_ld_odd
	global_load_dwordx4 v[104:107], v[2:3], off offset:1024
	global_load_dwordx4 v[108:111], v[2:3], off offset:1280
	s_branch .LBB0_323
.Lwin_ld_odd:
	global_load_dwordx4 v[100:103], v[2:3], off offset:1024
	global_load_dwordx4 v[96:99], v[2:3], off offset:1280
.LBB0_323:
	s_and_b32 s17, s14, 1
	s_mul_i32 s18, s17, 0x2400
	v_add_u32_e32 v139, s18, v128
	ds_read_b128 v[2:5], v139
	ds_read_b128 v[6:9], v139 offset:32
	s_cmp_lt_i32 s14, s10
	s_cselect_b64 s[4:5], -1, 0
	s_add_i32 s19, s6, s14
	s_waitcnt lgkmcnt(1)
	v_mfma_f32_32x32x16_bf16 v[64:79], v[2:5], v[80:83], v[16:31]
	ds_read_b128 v[2:5], v139 offset:64
	s_and_b32 s19, s19, 0x7ffffffb
	s_cmp_eq_u32 s19, 0
	s_cselect_b64 s[20:21], -1, 0
	s_and_b64 s[4:5], s[4:5], s[20:21]
	v_add_u32_e32 v154, s18, v129
	v_mov_b32_e32 v14, v0
	s_waitcnt lgkmcnt(1)
	v_mfma_f32_32x32x16_bf16 v[64:79], v[6:9], v[84:87], v[64:79]
	v_mov_b32_e32 v15, v0
	s_add_i32 s14, s14, 1
	s_waitcnt lgkmcnt(0)
	v_mfma_f32_32x32x16_bf16 v[64:79], v[2:5], v[88:91], v[64:79]
	ds_read_b128 v[2:5], v139 offset:96
	s_waitcnt lgkmcnt(0)
	v_mfma_f32_32x32x16_bf16 v[64:79], v[2:5], v[92:95], v[64:79]
	v_add_u32_e32 v2, 27, v131
	v_cmp_gt_u32_e32 vcc, s81, v2
	s_and_b64 s[20:21], s[4:5], vcc
	v_add_u32_e32 v2, 26, v131
	v_cmp_gt_u32_e32 vcc, s81, v2
	v_add_u32_e32 v2, 25, v131
	s_nop 5
	v_exp_f32_e32 v1, v64
	s_nop 0
	v_cndmask_b32_e64 v133, v1, 0, s[20:21]
	v_exp_f32_e32 v1, v65
	s_and_b64 s[20:21], s[4:5], vcc
	v_cmp_gt_u32_e32 vcc, s81, v2
	v_add_u32_e32 v2, 24, v131
	v_cndmask_b32_e64 v134, v1, 0, s[20:21]
	v_exp_f32_e32 v1, v66
	s_and_b64 s[20:21], s[4:5], vcc
	v_cmp_gt_u32_e32 vcc, s81, v2
	v_add_u32_e32 v2, 19, v131
	v_cndmask_b32_e64 v135, v1, 0, s[20:21]
	v_exp_f32_e32 v1, v67
	s_and_b64 s[20:21], s[4:5], vcc
	v_cmp_gt_u32_e32 vcc, s81, v2
	v_add_u32_e32 v2, 18, v131
	v_cndmask_b32_e64 v136, v1, 0, s[20:21]
	v_exp_f32_e32 v1, v68
	s_and_b64 s[20:21], s[4:5], vcc
	v_cmp_gt_u32_e32 vcc, s81, v2
	v_add_u32_e32 v2, 17, v131
	v_cndmask_b32_e64 v137, v1, 0, s[20:21]
	v_exp_f32_e32 v1, v69
	s_and_b64 s[20:21], s[4:5], vcc
	v_cmp_gt_u32_e32 vcc, s81, v2
	v_add_u32_e32 v2, 16, v131
	v_cndmask_b32_e64 v138, v1, 0, s[20:21]
	v_exp_f32_e32 v1, v70
	s_and_b64 s[20:21], s[4:5], vcc
	v_cmp_gt_u32_e32 vcc, s81, v2
	v_add_u32_e32 v2, 11, v131
	v_cndmask_b32_e64 v140, v1, 0, s[20:21]
	v_exp_f32_e32 v1, v71
	s_and_b64 s[20:21], s[4:5], vcc
	v_cmp_gt_u32_e32 vcc, s81, v2
	v_add_u32_e32 v2, 10, v131
	v_cndmask_b32_e64 v141, v1, 0, s[20:21]
	v_exp_f32_e32 v1, v72
	s_and_b64 s[20:21], s[4:5], vcc
	v_cmp_gt_u32_e32 vcc, s81, v2
	v_add_u32_e32 v2, 9, v131
	v_cndmask_b32_e64 v142, v1, 0, s[20:21]
	v_exp_f32_e32 v1, v73
	s_and_b64 s[20:21], s[4:5], vcc
	v_cmp_gt_u32_e32 vcc, s81, v2
	v_add_u32_e32 v2, 8, v131
	v_cndmask_b32_e64 v143, v1, 0, s[20:21]
	v_exp_f32_e32 v1, v74
	s_and_b64 s[20:21], s[4:5], vcc
	v_cmp_gt_u32_e32 vcc, s81, v2
	v_add_u32_e32 v2, 3, v131
	v_cndmask_b32_e64 v144, v1, 0, s[20:21]
	v_exp_f32_e32 v1, v75
	s_and_b64 s[20:21], s[4:5], vcc
	v_cmp_gt_u32_e32 vcc, s81, v2
	v_add_u32_e32 v2, 2, v131
	v_cndmask_b32_e64 v145, v1, 0, s[20:21]
	v_exp_f32_e32 v1, v76
	s_and_b64 s[20:21], s[4:5], vcc
	v_cmp_gt_u32_e32 vcc, s81, v2
	ds_read_b64_tr_b16 v[10:11], v154 offset:18432
	ds_read_b64_tr_b16 v[12:13], v154 offset:19584
	ds_read_b64_tr_b16 v[64:65], v154 offset:20736
	ds_read_b64_tr_b16 v[66:67], v154 offset:21888
	v_cndmask_b32_e64 v146, v1, 0, s[20:21]
	v_exp_f32_e32 v1, v77
	s_and_b64 s[20:21], s[4:5], vcc
	v_add_u32_e32 v2, 1, v131
	v_cmp_gt_u32_e32 vcc, s81, v2
	v_cndmask_b32_e64 v147, v1, 0, s[20:21]
	v_exp_f32_e32 v1, v78
	v_cvt_pk_bf16_f32 v2, v133, v134
	v_cvt_pk_bf16_f32 v3, v135, v136
	v_cvt_pk_bf16_f32 v4, v137, v138
	v_cvt_pk_bf16_f32 v5, v140, v141
	s_and_b64 s[20:21], s[4:5], vcc
	v_cndmask_b32_e64 v148, v1, 0, s[20:21]
	s_waitcnt lgkmcnt(2)
	v_mfma_f32_32x32x16_bf16 v[48:63], v[10:13], v[2:5], v[48:63]
	v_exp_f32_e32 v1, v79
	v_cmp_gt_u32_e32 vcc, s81, v131
	s_and_b64 s[20:21], s[4:5], vcc
	v_cvt_pk_bf16_f32 v6, v142, v143
	v_cndmask_b32_e64 v149, v1, 0, s[20:21]
	v_cvt_pk_bf16_f32 v7, v144, v145
	v_cvt_pk_bf16_f32 v8, v146, v147
	v_cvt_pk_bf16_f32 v9, v148, v149
	v_mov_b32_e32 v1, v0
	s_waitcnt lgkmcnt(0)
	v_mfma_f32_32x32x16_bf16 v[48:63], v[64:67], v[6:9], v[48:63]
	ds_read_b64_tr_b16 v[10:11], v154 offset:18496
	ds_read_b64_tr_b16 v[12:13], v154 offset:19648
	ds_read_b64_tr_b16 v[64:65], v154 offset:20800
	ds_read_b64_tr_b16 v[66:67], v154 offset:21952
	ds_read_b128 v[150:153], v139 offset:4608
	s_waitcnt lgkmcnt(3)
; #define LAS __attribute__((address_space(3)))
; #define MFMA32(a, b, c) __builtin_amdgcn_mfma_f32_32x32x16_bf16((a), (b), (c), 0, 0, 0)
; #define PACK8(x, s) __builtin_bit_cast(bf16x8, (v4u){pkbf((x)[8 * (s)], (x)[8 * (s) + 1]), pkbf((x)[8 * (s) + 2], (x)[8 * (s) + 3]), pkbf((x)[8 * (s) + 4], (x)[8 * (s) + 5]), pkbf((x)[8 * (s) + 6], (x)[8 * (s) + 7])})
; DI void win_mfma_phase(const Args& A, int wave_s, int l, bool need_ctx, LAS unsigned char* lds) {
;     ...
; #pragma unroll
;             for (int sub = 0; sub < 2; ++sub) {
;                 f32x16 S;
; #pragma unroll
;                 for (int i = 0; i < 16; ++i) S[i] = -Mb2;
; #pragma unroll
;                 for (int s = 0; s < 4; ++s) { const bf16x8 kf = *(LAS bf16x8*)(Kb + (32 * sub + r) * KV_PITCH + s * 32 + h * 16); S = MFMA32(kf, Qf[s], S); }
;                 float t = 0.f;
; #pragma unroll
;                 for (int i = 0; i < 16; ++i) { float e = __builtin_amdgcn_exp2f(S[i]);
;                     if (edge) { const int tk = tk0 + 32 * sub + (i & 3) + 8 * (i >> 2) + 4 * h; const int d = tq - tk; e = (d > 128 || d < -128) ? 0.f : e; }
;                     S[i] = e; t += e; }
;                 ls += t;
;                 const bf16x8 P0 = PACK8(S, 0), P1 = PACK8(S, 1);
; #pragma unroll
;                 for (int mt = 0; mt < 2; ++mt) {
;                     const bf16x8 v0 = tr_pair(Vb + (32 * sub) * KV_PITCH + voff + mt * 64);
;                     const bf16x8 v1 = tr_pair(Vb + (32 * sub + 16) * KV_PITCH + voff + mt * 64);
;                     O[mt] = MFMA32(v0, P0, O[mt]); O[mt] = MFMA32(v1, P1, O[mt]);
;                 }
;             }
;             if (it + 1 < ntiles) { *(LAS v4u*)(lds + (cur ^ 1) * KV_IMG + srow * KV_PITCH + sch * 16) = kreg; *(LAS v4u*)(lds + 2 * KV_IMG + (cur ^ 1) * KV_IMG + srow * KV_PITCH + sch * 16) = vreg; kreg = kreg2; vreg = vreg2; }
	v_mfma_f32_32x32x16_bf16 v[32:47], v[10:13], v[2:5], v[32:47]
	v_mov_b32_e32 v2, v0
	v_mov_b32_e32 v3, v0
	v_mov_b32_e32 v4, v0
	v_mov_b32_e32 v5, v0
	v_mov_b32_e32 v10, v0
	v_mov_b32_e32 v11, v0
	v_mov_b32_e32 v12, v0
	s_waitcnt lgkmcnt(1)
	v_mfma_f32_32x32x16_bf16 v[32:47], v[64:67], v[6:9], v[32:47]
	v_mov_b32_e32 v6, v0
	v_mov_b32_e32 v7, v0
	v_mov_b32_e32 v8, v0
	v_mov_b32_e32 v9, v0
	v_mov_b32_e32 v13, v0
	v_mov_b64_e32 v[78:79], v[14:15]
	v_mov_b64_e32 v[76:77], v[12:13]
	v_mov_b64_e32 v[74:75], v[10:11]
	v_mov_b64_e32 v[72:73], v[8:9]
	v_mov_b64_e32 v[70:71], v[6:7]
	v_mov_b64_e32 v[68:69], v[4:5]
	v_mov_b64_e32 v[66:67], v[2:3]
	v_mov_b64_e32 v[64:65], v[0:1]
	ds_read_b128 v[2:5], v139 offset:4640
	v_add_u32_e32 v6, -13, v131
	s_waitcnt lgkmcnt(1)
	v_mfma_f32_32x32x16_bf16 v[64:79], v[150:153], v[80:83], v[64:79]
	v_add_u32_e32 v7, -14, v131
	v_add_u32_e32 v8, -15, v131
	v_add_u32_e32 v9, -16, v131
	v_subrev_u32_e32 v10, 21, v131
	v_subrev_u32_e32 v11, 22, v131
	v_subrev_u32_e32 v12, 23, v131
	v_subrev_u32_e32 v13, 24, v131
	s_waitcnt lgkmcnt(0)
	v_mfma_f32_32x32x16_bf16 v[64:79], v[2:5], v[84:87], v[64:79]
	ds_read_b128 v[2:5], v139 offset:4672
	v_subrev_u32_e32 v14, 29, v131
	v_subrev_u32_e32 v15, 30, v131
	s_waitcnt lgkmcnt(0)
	v_mfma_f32_32x32x16_bf16 v[64:79], v[2:5], v[88:91], v[64:79]
	ds_read_b128 v[2:5], v139 offset:4704
	s_waitcnt lgkmcnt(0)
	v_mfma_f32_32x32x16_bf16 v[64:79], v[2:5], v[92:95], v[64:79]
	v_add_u32_e32 v2, -5, v131
	v_cmp_gt_u32_e32 vcc, s81, v2
	v_add_u32_e32 v3, -6, v131
	s_and_b64 s[18:19], s[4:5], vcc
	v_cmp_gt_u32_e32 vcc, s81, v3
	v_add_u32_e32 v4, -7, v131
	v_add_u32_e32 v5, -8, v131
	s_nop 4
	v_exp_f32_e32 v1, v64
	v_exp_f32_e32 v2, v65
	v_exp_f32_e32 v3, v66
	v_subrev_u32_e32 v64, 31, v131
	v_cndmask_b32_e64 v1, v1, 0, s[18:19]
	s_and_b64 s[18:19], s[4:5], vcc
	v_cmp_gt_u32_e32 vcc, s81, v4
	v_exp_f32_e32 v4, v67
	v_cndmask_b32_e64 v2, v2, 0, s[18:19]
	s_and_b64 s[18:19], s[4:5], vcc
	v_cmp_gt_u32_e32 vcc, s81, v5
	v_exp_f32_e32 v5, v68
	v_cndmask_b32_e64 v3, v3, 0, s[18:19]
	s_and_b64 s[18:19], s[4:5], vcc
	v_cmp_gt_u32_e32 vcc, s81, v6
	v_exp_f32_e32 v6, v69
	v_cndmask_b32_e64 v4, v4, 0, s[18:19]
	s_and_b64 s[18:19], s[4:5], vcc
	v_cmp_gt_u32_e32 vcc, s81, v7
	v_exp_f32_e32 v7, v70
	v_cndmask_b32_e64 v5, v5, 0, s[18:19]
	s_and_b64 s[18:19], s[4:5], vcc
	v_cmp_gt_u32_e32 vcc, s81, v8
	v_exp_f32_e32 v8, v71
	v_cndmask_b32_e64 v6, v6, 0, s[18:19]
	s_and_b64 s[18:19], s[4:5], vcc
	v_cmp_gt_u32_e32 vcc, s81, v9
	v_exp_f32_e32 v9, v72
	v_cndmask_b32_e64 v7, v7, 0, s[18:19]
	s_and_b64 s[18:19], s[4:5], vcc
	v_cmp_gt_u32_e32 vcc, s81, v10
	v_exp_f32_e32 v10, v73
	v_cndmask_b32_e64 v8, v8, 0, s[18:19]
	s_and_b64 s[18:19], s[4:5], vcc
	v_cmp_gt_u32_e32 vcc, s81, v11
	v_exp_f32_e32 v11, v74
	v_cndmask_b32_e64 v9, v9, 0, s[18:19]
	s_and_b64 s[18:19], s[4:5], vcc
	v_cmp_gt_u32_e32 vcc, s81, v12
	v_cndmask_b32_e64 v10, v10, 0, s[18:19]
	s_and_b64 s[18:19], s[4:5], vcc
	v_cmp_gt_u32_e32 vcc, s81, v13
	v_cndmask_b32_e64 v11, v11, 0, s[18:19]
	v_exp_f32_e32 v12, v75
	s_and_b64 s[18:19], s[4:5], vcc
	v_exp_f32_e32 v13, v76
	v_cmp_gt_u32_e32 vcc, s81, v14
	v_exp_f32_e32 v14, v77
	ds_read_b64_tr_b16 v[74:75], v154 offset:23040
	ds_read_b64_tr_b16 v[76:77], v154 offset:24192
	ds_read_b64_tr_b16 v[150:151], v154 offset:25344
	ds_read_b64_tr_b16 v[152:153], v154 offset:26496
	v_cvt_pk_bf16_f32 v66, v1, v2
	v_cvt_pk_bf16_f32 v67, v3, v4
	v_cvt_pk_bf16_f32 v68, v5, v6
	v_cvt_pk_bf16_f32 v69, v7, v8
	v_cndmask_b32_e64 v12, v12, 0, s[18:19]
	s_and_b64 s[18:19], s[4:5], vcc
	s_waitcnt lgkmcnt(2)
	v_mfma_f32_32x32x16_bf16 v[48:63], v[74:77], v[66:69], v[48:63]
	v_cmp_gt_u32_e32 vcc, s81, v15
	v_cndmask_b32_e64 v13, v13, 0, s[18:19]
	s_and_b64 s[18:19], s[4:5], vcc
	v_exp_f32_e32 v15, v78
	v_cmp_gt_u32_e32 vcc, s81, v64
	v_exp_f32_e32 v64, v79
	v_subrev_u32_e32 v65, 32, v131
	v_cndmask_b32_e64 v14, v14, 0, s[18:19]
	s_and_b64 s[18:19], s[4:5], vcc
	v_cmp_gt_u32_e32 vcc, s81, v65
	s_and_b64 s[4:5], s[4:5], vcc
	v_cndmask_b32_e64 v15, v15, 0, s[18:19]
	v_cndmask_b32_e64 v64, v64, 0, s[4:5]
	v_cvt_pk_bf16_f32 v70, v9, v10
	v_cvt_pk_bf16_f32 v71, v11, v12
	v_cvt_pk_bf16_f32 v72, v13, v14
	v_cvt_pk_bf16_f32 v73, v15, v64
	s_cmp_ge_i32 s14, s12
	s_waitcnt lgkmcnt(0)
	v_mfma_f32_32x32x16_bf16 v[48:63], v[150:153], v[70:73], v[48:63]
	ds_read_b64_tr_b16 v[74:75], v154 offset:23104
	ds_read_b64_tr_b16 v[76:77], v154 offset:24256
	ds_read_b64_tr_b16 v[150:151], v154 offset:25408
	ds_read_b64_tr_b16 v[152:153], v154 offset:26560
	s_waitcnt lgkmcnt(2)
	v_mfma_f32_32x32x16_bf16 v[32:47], v[74:77], v[66:69], v[32:47]
	s_waitcnt lgkmcnt(0)
	v_mfma_f32_32x32x16_bf16 v[32:47], v[150:153], v[70:73], v[32:47]
	s_cbranch_scc1 .LBB0_320
	s_xor_b32 s4, s17, 1
	s_mulk_i32 s4, 0x2400
	v_add_u32_e32 v65, s4, v127
	s_add_i32 s4, s14, 1
	s_cmp_ge_i32 s4, s12
	s_cbranch_scc1 .Lwin_w0
	s_waitcnt vmcnt(2)
	s_branch .Lwin_wd

; #define LAS __attribute__((address_space(3)))
; DI void win_mfma_phase(const Args& A, int wave_s, int l, bool need_ctx, LAS unsigned char* lds) {
;     ...
;             if (it + 1 < ntiles) { *(LAS v4u*)(lds + (cur ^ 1) * KV_IMG + srow * KV_PITCH + sch * 16) = kreg; *(LAS v4u*)(lds + 2 * KV_IMG + (cur ^ 1) * KV_IMG + srow * KV_PITCH + sch * 16) = vreg; kreg = kreg2; vreg = vreg2; }
.Lwin_wd:
	s_cmp_eq_u32 s17, 0
	s_cbranch_scc0 .Lwin_st_y
	ds_write_b128 v65, v[100:103]
	ds_write_b128 v65, v[96:99] offset:18432
	s_branch .LBB0_320
.Lwin_st_y:
	ds_write_b128 v65, v[104:107]
	ds_write_b128 v65, v[108:111] offset:18432
	s_branch .LBB0_320
